# prefetch of the other three ssq row tiles when the first rstd-table sub-block loads (A and D preambles)
# baseline (speedup 1.0000x reference)
;     __device__ __forceinline__ bool next(int i, Unit& u) const { if (i >= n) return false; int o = own; asm volatile("" : "+s"(o)); u.pm = swap ? i : o; u.pn = swap ? o : i; u.idx = i; return true; }
;     __device__ __forceinline__ bool next(int i, Unit& u) const {
;         const int L = i * G + c; if (L >= nwg) return false;
;         int wgid = L; { const int q = nwg / NXCD, r = nwg % NXCD, xcd = wgid % NXCD, off = wgid / NXCD; wgid = (xcd < r ? xcd * (q + 1) : r * (q + 1) + (xcd - r) * q) + off; }
;         const int nig = WGM * nN, gid = wgid / nig, fm = gid * WGM, gsz = (nM - fm) < WGM ? (nM - fm) : WGM;
;         u.pm = fm + ((wgid % nig) % gsz); u.pn = (wgid % nig) / gsz; u.idx = i; return true;
;     }
.LBB0_160:
	s_or_b64 exec, exec, s[28:29]
	s_xor_b64 s[28:29], s[92:93], -1
	v_and_b32_e32 v5, 0xff, v130
	v_writelane_b32 v254, s28, 11
	v_lshlrev_b32_e32 v0, 6, v5
	v_lshl_add_u64 v[2:3], s[22:23], 0, v[0:1]
	v_writelane_b32 v254, s29, 12
	s_mov_b64 s[28:29], 0x3000000
	v_ashrrev_i32_e32 v193, 31, v192
	v_lshl_add_u64 v[2:3], v[2:3], 0, s[28:29]
	v_lshlrev_b64 v[8:9], 14, v[192:193]
	v_lshl_add_u64 v[20:21], v[2:3], 0, v[8:9]
	global_load_dwordx4 v[8:11], v[20:21], off offset:48
	global_load_dwordx4 v[12:15], v[20:21], off offset:32
	global_load_dwordx4 v[16:19], v[20:21], off offset:16
	s_nop 0
	s_mov_b64 s[98:99], 0x20000
	v_lshl_add_u64 v[28:29], v[20:21], 0, s[98:99]
	global_load_dword v30, v[28:29], off
	v_lshl_add_u64 v[28:29], v[28:29], 0, s[98:99]
	global_load_dword v30, v[28:29], off
	v_lshl_add_u64 v[28:29], v[28:29], 0, s[98:99]
	global_load_dword v30, v[28:29], off
	global_load_dwordx4 v[20:23], v[20:21], off
	v_readlane_b32 s28, v254, 9
	v_add_u32_e32 v4, s48, v4
	s_waitcnt vmcnt(2)
	v_add_f32_e32 v12, v12, v13
	v_lshl_add_u32 v0, v5, 2, s28
	s_waitcnt vmcnt(0)
	v_mov_b32_e32 v24, v21
	v_mov_b32_e32 v25, v22
	v_mov_b32_e32 v21, v23
	v_mov_b32_e32 v22, v17
	v_mov_b32_e32 v23, v18
	v_mov_b32_e32 v17, v19
	v_pk_add_f32 v[20:21], v[24:25], v[20:21]
	v_pk_add_f32 v[16:17], v[22:23], v[16:17]
	v_add_f32_e32 v5, v20, v21
	v_pk_add_f32 v[16:17], v[16:17], v[16:17] op_sel:[0,1] op_sel_hi:[1,0]
	v_add_f32_e32 v20, 0, v5
	v_add_f32_e32 v14, v14, v15
	v_mov_b32_e32 v21, v8
	v_mov_b32_e32 v17, v9
	v_mov_b32_e32 v13, v10
	v_mov_b32_e32 v15, v11
	v_pk_add_f32 v[8:9], v[20:21], v[16:17]
	v_pk_add_f32 v[10:11], v[12:13], v[14:15]
	v_lshl_add_u32 v0, v6, 10, v0
	v_pk_add_f32 v[8:9], v[8:9], v[10:11]
	s_nop 0
	v_add_f32_e32 v5, v8, v9
	v_fmamk_f32 v5, v5, 0x3a800000, v231
	v_cmp_gt_f32_e32 vcc, s30, v5
	v_mul_f32_e32 v7, 0x4f800000, v5
	s_nop 0
	v_cndmask_b32_e32 v5, v5, v7, vcc
	v_sqrt_f32_e32 v7, v5
	s_nop 0
	v_add_u32_e32 v8, -1, v7
	v_fma_f32 v9, -v8, v7, v5
	v_cmp_ge_f32_e64 s[36:37], 0, v9
	v_add_u32_e32 v9, 1, v7
	s_nop 0
	v_cndmask_b32_e64 v8, v7, v8, s[36:37]
	v_fma_f32 v7, -v9, v7, v5
	v_cmp_lt_f32_e64 s[36:37], 0, v7
	s_nop 1
	v_cndmask_b32_e64 v7, v8, v9, s[36:37]
	v_mul_f32_e32 v8, 0x37800000, v7
	v_cndmask_b32_e32 v7, v7, v8, vcc
	v_cmp_class_f32_e32 vcc, v5, v232
	s_nop 1
	v_cndmask_b32_e32 v5, v7, v5, vcc
	v_div_scale_f32 v7, s[28:29], v5, v5, 1.0
	v_rcp_f32_e32 v8, v7
	s_nop 0
	v_fma_f32 v9, -v7, v8, 1.0
	v_fmac_f32_e32 v8, v9, v8
	v_div_scale_f32 v9, vcc, 1.0, v5, 1.0
	v_mul_f32_e32 v10, v9, v8
	v_fma_f32 v11, -v7, v10, v9
	v_fmac_f32_e32 v10, v11, v8
	v_fma_f32 v7, -v7, v10, v9
	v_div_fmas_f32 v7, v7, v8, v10
	v_div_fixup_f32 v5, v7, v5, 1.0
	v_cmp_gt_i32_e32 vcc, s49, v4
	ds_write_b32 v0, v5
	s_and_saveexec_b64 s[28:29], vcc
	s_cbranch_execz .LBB0_166
	v_ashrrev_i32_e32 v5, 31, v4
	v_lshrrev_b32_e32 v5, 29, v5
	v_add_u32_e32 v5, v4, v5
	v_and_b32_e32 v6, -8, v5
	v_sub_u32_e32 v7, v4, v6
	v_cmp_lt_i32_e32 vcc, -1, v7
	s_and_saveexec_b64 s[36:37], vcc
	s_xor_b64 s[36:37], exec, s[36:37]
	v_lshlrev_b32_e32 v6, 8, v7
	s_andn2_saveexec_b64 s[36:37], s[36:37]
	v_lshl_add_u32 v6, v7, 8, v7
	s_or_b64 exec, exec, s[36:37]
	v_ashrrev_i32_e32 v5, 3, v5
	v_add_u32_e32 v5, v6, v5
	v_ashrrev_i32_e32 v6, 31, v5
	v_lshrrev_b32_e32 v6, 26, v6
	v_add_u32_e32 v6, v5, v6
	v_ashrrev_i32_e32 v7, 6, v6
	v_and_b32_e32 v6, 0xffc0, v6
	v_sub_u32_e32 v5, v5, v6
	v_lshrrev_b16_sdwa v6, v234, sext(v5) dst_sel:DWORD dst_unused:UNUSED_PAD src0_sel:DWORD src1_sel:BYTE_0
	v_and_b32_e32 v6, 7, v6
	v_add_u16_e32 v6, v5, v6
	v_and_b32_e32 v6, 0xf8, v6
	v_sub_u16_e32 v5, v5, v6
	v_bfe_i32 v5, v5, 0, 8
	v_lshl_add_u32 v192, v7, 3, v5
	v_ashrrev_i32_e32 v193, 31, v192
	v_lshlrev_b64 v[6:7], 14, v[192:193]
	v_lshl_add_u64 v[18:19], v[2:3], 0, v[6:7]
	global_load_dwordx4 v[6:9], v[18:19], off offset:48
	global_load_dwordx4 v[10:13], v[18:19], off offset:32
	global_load_dwordx4 v[14:17], v[18:19], off offset:16
	s_nop 0
	global_load_dwordx4 v[18:21], v[18:19], off
	s_waitcnt vmcnt(2)
	v_add_f32_e32 v10, v10, v11
	v_add_f32_e32 v12, v12, v13
	s_waitcnt vmcnt(0)
	v_mov_b32_e32 v22, v19
	v_mov_b32_e32 v23, v20
	v_mov_b32_e32 v19, v21
	v_mov_b32_e32 v20, v15
	v_mov_b32_e32 v21, v16
	v_mov_b32_e32 v15, v17
	v_pk_add_f32 v[18:19], v[22:23], v[18:19]
	v_pk_add_f32 v[14:15], v[20:21], v[14:15]
	v_add_f32_e32 v5, v18, v19
	v_pk_add_f32 v[14:15], v[14:15], v[14:15] op_sel:[0,1] op_sel_hi:[1,0]
	v_add_f32_e32 v18, 0, v5
	v_mov_b32_e32 v19, v6
	v_mov_b32_e32 v15, v7
	v_mov_b32_e32 v11, v8
	v_mov_b32_e32 v13, v9
	v_pk_add_f32 v[6:7], v[18:19], v[14:15]
	v_pk_add_f32 v[8:9], v[10:11], v[12:13]
	s_nop 0
	v_pk_add_f32 v[6:7], v[6:7], v[8:9]
	s_nop 0
	v_add_f32_e32 v5, v6, v7
	v_fmamk_f32 v5, v5, 0x3a800000, v231
	v_cmp_gt_f32_e32 vcc, s30, v5
	v_mul_f32_e32 v6, 0x4f800000, v5
	s_nop 0
	v_cndmask_b32_e32 v5, v5, v6, vcc
	v_sqrt_f32_e32 v6, v5
	s_nop 0
	v_add_u32_e32 v7, -1, v6
	v_fma_f32 v8, -v7, v6, v5
	v_cmp_ge_f32_e64 s[36:37], 0, v8
	v_add_u32_e32 v8, 1, v6
	s_nop 0
	v_cndmask_b32_e64 v7, v6, v7, s[36:37]
	v_fma_f32 v6, -v8, v6, v5
	v_cmp_lt_f32_e64 s[36:37], 0, v6
	s_nop 1
	v_cndmask_b32_e64 v6, v7, v8, s[36:37]
	v_mul_f32_e32 v7, 0x37800000, v6
	v_cndmask_b32_e32 v6, v6, v7, vcc
	v_cmp_class_f32_e32 vcc, v5, v232
	s_nop 1
	v_cndmask_b32_e32 v5, v6, v5, vcc
	v_div_scale_f32 v6, s[36:37], v5, v5, 1.0
	v_rcp_f32_e32 v7, v6
	s_nop 0
	v_fma_f32 v8, -v6, v7, 1.0
	v_fmac_f32_e32 v7, v8, v7
	v_div_scale_f32 v8, vcc, 1.0, v5, 1.0
	v_mul_f32_e32 v9, v8, v7
	v_fma_f32 v10, -v6, v9, v8
	v_fmac_f32_e32 v9, v10, v7
	v_fma_f32 v6, -v6, v9, v8
	v_div_fmas_f32 v6, v6, v7, v9
	v_div_fixup_f32 v5, v6, v5, 1.0

;     __device__ __forceinline__ bool next(int i, Unit& u) const { if (i >= n) return false; int o = own; asm volatile("" : "+s"(o)); u.pm = swap ? i : o; u.pn = swap ? o : i; u.idx = i; return true; }
;     __device__ __forceinline__ bool next(int i, Unit& u) const {
;         const int L = i * G + c; if (L >= nwg) return false;
;         int wgid = L; { const int q = nwg / NXCD, r = nwg % NXCD, xcd = wgid % NXCD, off = wgid / NXCD; wgid = (xcd < r ? xcd * (q + 1) : r * (q + 1) + (xcd - r) * q) + off; }
;         const int nig = WGM * nN, gid = wgid / nig, fm = gid * WGM, gsz = (nM - fm) < WGM ? (nM - fm) : WGM;
;         u.pm = fm + ((wgid % nig) % gsz); u.pn = (wgid % nig) / gsz; u.idx = i; return true;
;     }
.LBB0_462:
	s_or_b64 exec, exec, s[22:23]
	v_ashrrev_i32_e32 v195, 31, v194
	v_lshlrev_b64 v[8:9], 14, v[194:195]
	v_lshl_add_u64 v[22:23], v[2:3], 0, v[8:9]
	global_load_dwordx4 v[8:11], v[22:23], off offset:48
	global_load_dwordx4 v[14:17], v[22:23], off offset:32
	global_load_dwordx4 v[18:21], v[22:23], off offset:16
	s_nop 0
	s_cmp_lt_i32 s38, 0
	s_cbranch_scc0 .Lpf_skip_D
	s_mov_b64 s[98:99], 0x20000
	v_lshl_add_u64 v[28:29], v[22:23], 0, s[98:99]
	global_load_dword v30, v[28:29], off
	v_lshl_add_u64 v[28:29], v[28:29], 0, s[98:99]
	global_load_dword v30, v[28:29], off
	v_lshl_add_u64 v[28:29], v[28:29], 0, s[98:99]
	global_load_dword v30, v[28:29], off
.Lpf_skip_D:
	global_load_dwordx4 v[22:25], v[22:23], off
	s_waitcnt vmcnt(2)
	v_add_f32_e32 v14, v14, v15
	v_add_f32_e32 v16, v16, v17
	s_waitcnt vmcnt(0)
	v_mov_b32_e32 v26, v23
	v_mov_b32_e32 v27, v24
	v_mov_b32_e32 v23, v25
	v_mov_b32_e32 v24, v19
	v_mov_b32_e32 v25, v20
	v_mov_b32_e32 v19, v21
	v_pk_add_f32 v[22:23], v[26:27], v[22:23]
	v_pk_add_f32 v[18:19], v[24:25], v[18:19]
	v_add_f32_e32 v13, v22, v23
	v_pk_add_f32 v[18:19], v[18:19], v[18:19] op_sel:[0,1] op_sel_hi:[1,0]
	v_add_f32_e32 v22, 0, v13
	v_mov_b32_e32 v23, v8
	v_mov_b32_e32 v19, v9
	v_mov_b32_e32 v15, v10
	v_mov_b32_e32 v17, v11
	v_pk_add_f32 v[8:9], v[22:23], v[18:19]
	v_pk_add_f32 v[10:11], v[14:15], v[16:17]
	s_nop 0
	v_pk_add_f32 v[8:9], v[8:9], v[10:11]
	s_nop 0
	v_add_f32_e32 v8, v8, v9
	v_fmamk_f32 v8, v8, 0x3a800000, v231
	v_cmp_gt_f32_e32 vcc, s30, v8
	v_mul_f32_e32 v9, 0x4f800000, v8
	s_nop 0
	v_cndmask_b32_e32 v8, v8, v9, vcc
	v_sqrt_f32_e32 v9, v8
	s_nop 0
	v_add_u32_e32 v10, -1, v9
	v_fma_f32 v11, -v10, v9, v8
	v_cmp_ge_f32_e64 s[40:41], 0, v11
	v_add_u32_e32 v11, 1, v9
	s_nop 0
	v_cndmask_b32_e64 v10, v9, v10, s[40:41]
	v_fma_f32 v9, -v11, v9, v8
	v_cmp_lt_f32_e64 s[40:41], 0, v9
	s_nop 1
	v_cndmask_b32_e64 v9, v10, v11, s[40:41]
	v_mul_f32_e32 v10, 0x37800000, v9
	v_cndmask_b32_e32 v9, v9, v10, vcc
	v_cmp_class_f32_e32 vcc, v8, v232
	s_nop 1
	v_cndmask_b32_e32 v8, v9, v8, vcc
	v_div_scale_f32 v9, s[22:23], v8, v8, 1.0
	v_rcp_f32_e32 v10, v9
	s_nop 0
	v_fma_f32 v11, -v9, v10, 1.0
	v_fmac_f32_e32 v10, v11, v10
	v_div_scale_f32 v11, vcc, 1.0, v8, 1.0
	v_mul_f32_e32 v13, v11, v10
	v_fma_f32 v14, -v9, v13, v11
	v_fmac_f32_e32 v13, v14, v10
	v_fma_f32 v9, -v9, v13, v11
	v_div_fmas_f32 v9, v9, v10, v13
	v_div_fixup_f32 v8, v9, v8, 1.0
	v_add_u32_e32 v9, s39, v6
	v_cmp_gt_i32_e32 vcc, s25, v9
	ds_write_b32 v0, v8
	s_and_saveexec_b64 s[22:23], vcc
	s_cbranch_execz .LBB0_468
	v_ashrrev_i32_e32 v8, 31, v9
	v_lshrrev_b32_e32 v8, 29, v8
	v_add_u32_e32 v8, v9, v8
	v_and_b32_e32 v10, -8, v8
	v_sub_u32_e32 v10, v9, v10
	v_cmp_lt_i32_e32 vcc, -1, v10
	s_and_saveexec_b64 s[40:41], vcc
	s_xor_b64 s[40:41], exec, s[40:41]
	v_lshlrev_b32_e32 v9, 9, v10
	s_andn2_saveexec_b64 s[40:41], s[40:41]
	v_lshl_add_u32 v9, v10, 9, v10
	s_or_b64 exec, exec, s[40:41]
	v_ashrrev_i32_e32 v8, 3, v8
	v_add_u32_e32 v8, v9, v8
	v_ashrrev_i32_e32 v9, 31, v8
	v_lshrrev_b32_e32 v9, 25, v9
	v_add_u32_e32 v9, v8, v9
	v_ashrrev_i32_e32 v10, 7, v9
	v_and_b32_e32 v9, 0xff80, v9
	v_sub_u32_e32 v8, v8, v9
	v_lshrrev_b16_sdwa v9, v234, sext(v8) dst_sel:DWORD dst_unused:UNUSED_PAD src0_sel:DWORD src1_sel:BYTE_0
	v_and_b32_e32 v9, 7, v9
	v_add_u16_e32 v9, v8, v9
	v_and_b32_e32 v9, 0xf8, v9
	v_sub_u16_e32 v8, v8, v9
	v_bfe_i32 v8, v8, 0, 8
	v_lshl_add_u32 v194, v10, 3, v8
	v_ashrrev_i32_e32 v195, 31, v194
	v_lshlrev_b64 v[8:9], 14, v[194:195]
	v_lshl_add_u64 v[22:23], v[2:3], 0, v[8:9]
	global_load_dwordx4 v[8:11], v[22:23], off offset:48
	global_load_dwordx4 v[14:17], v[22:23], off offset:32
	global_load_dwordx4 v[18:21], v[22:23], off offset:16
	s_nop 0
	global_load_dwordx4 v[22:25], v[22:23], off
	s_waitcnt vmcnt(2)
	v_add_f32_e32 v14, v14, v15
	v_add_f32_e32 v16, v16, v17
	s_waitcnt vmcnt(0)
	v_mov_b32_e32 v26, v23
	v_mov_b32_e32 v27, v24
	v_mov_b32_e32 v23, v25
	v_mov_b32_e32 v24, v19
	v_mov_b32_e32 v25, v20
	v_mov_b32_e32 v19, v21
	v_pk_add_f32 v[22:23], v[26:27], v[22:23]
	v_pk_add_f32 v[18:19], v[24:25], v[18:19]
	v_add_f32_e32 v13, v22, v23
	v_pk_add_f32 v[18:19], v[18:19], v[18:19] op_sel:[0,1] op_sel_hi:[1,0]
	v_add_f32_e32 v22, 0, v13
	v_mov_b32_e32 v23, v8
	v_mov_b32_e32 v19, v9
	v_mov_b32_e32 v15, v10
	v_mov_b32_e32 v17, v11
	v_pk_add_f32 v[8:9], v[22:23], v[18:19]
	v_pk_add_f32 v[10:11], v[14:15], v[16:17]
	s_nop 0
	v_pk_add_f32 v[8:9], v[8:9], v[10:11]
	s_nop 0
	v_add_f32_e32 v8, v8, v9
	v_fmamk_f32 v8, v8, 0x3a800000, v231
	v_cmp_gt_f32_e32 vcc, s30, v8
	v_mul_f32_e32 v9, 0x4f800000, v8
	s_nop 0
	v_cndmask_b32_e32 v8, v8, v9, vcc
	v_sqrt_f32_e32 v9, v8
	s_nop 0
	v_add_u32_e32 v10, -1, v9
	v_fma_f32 v11, -v10, v9, v8
	v_cmp_ge_f32_e64 s[40:41], 0, v11
	v_add_u32_e32 v11, 1, v9
	s_nop 0
	v_cndmask_b32_e64 v10, v9, v10, s[40:41]
	v_fma_f32 v9, -v11, v9, v8
	v_cmp_lt_f32_e64 s[40:41], 0, v9
	s_nop 1
	v_cndmask_b32_e64 v9, v10, v11, s[40:41]
	v_mul_f32_e32 v10, 0x37800000, v9
	v_cndmask_b32_e32 v9, v9, v10, vcc
	v_cmp_class_f32_e32 vcc, v8, v232
	s_nop 1
	v_cndmask_b32_e32 v8, v9, v8, vcc
	v_div_scale_f32 v9, s[40:41], v8, v8, 1.0
	v_rcp_f32_e32 v10, v9
	s_nop 0
	v_fma_f32 v11, -v9, v10, 1.0
	v_fmac_f32_e32 v10, v11, v10
	v_div_scale_f32 v11, vcc, 1.0, v8, 1.0
	v_mul_f32_e32 v13, v11, v10
	v_fma_f32 v14, -v9, v13, v11
	v_fmac_f32_e32 v13, v14, v10
	v_fma_f32 v9, -v9, v13, v11
	v_div_fmas_f32 v9, v9, v10, v13
	v_div_fixup_f32 v8, v9, v8, 1.0

; __global__ void __launch_bounds__(NTHREADS, 2) trunk_fwd(Args a) {
;     extern __shared__ __attribute__((aligned(16))) unsigned char lds_raw[];
	.amdhsa_kernel _Z9trunk_fwd4Args
		.amdhsa_group_segment_fixed_size 0
		.amdhsa_private_segment_fixed_size 0
		.amdhsa_kernarg_size 368
		.amdhsa_user_sgpr_count 2
		.amdhsa_user_sgpr_dispatch_ptr 0
		.amdhsa_user_sgpr_queue_ptr 0
		.amdhsa_user_sgpr_kernarg_segment_ptr 1
		.amdhsa_user_sgpr_dispatch_id 0
		.amdhsa_user_sgpr_kernarg_preload_length 0
		.amdhsa_user_sgpr_kernarg_preload_offset 0
		.amdhsa_user_sgpr_private_segment_size 0
		.amdhsa_uses_dynamic_stack 0
		.amdhsa_enable_private_segment 0
		.amdhsa_system_sgpr_workgroup_id_x 1
		.amdhsa_system_sgpr_workgroup_id_y 0
		.amdhsa_system_sgpr_workgroup_id_z 0
		.amdhsa_system_sgpr_workgroup_info 0
		.amdhsa_system_vgpr_workitem_id 2
		.amdhsa_next_free_vgpr 256
		.amdhsa_next_free_sgpr 102
		.amdhsa_accum_offset 256
		.amdhsa_reserve_vcc 1
		.amdhsa_float_round_mode_32 0
		.amdhsa_float_round_mode_16_64 0
		.amdhsa_float_denorm_mode_32 3
		.amdhsa_float_denorm_mode_16_64 3
		.amdhsa_dx10_clamp 1
		.amdhsa_ieee_mode 1
		.amdhsa_fp16_overflow 0
		.amdhsa_tg_split 0
		.amdhsa_exception_fp_ieee_invalid_op 0
		.amdhsa_exception_fp_denorm_src 0
		.amdhsa_exception_fp_ieee_div_zero 0
		.amdhsa_exception_fp_ieee_overflow 0
		.amdhsa_exception_fp_ieee_underflow 0
		.amdhsa_exception_fp_ieee_inexact 0
		.amdhsa_exception_int_div_zero 0
	.end_amdhsa_kernel

; __global__ void __launch_bounds__(NTHREADS, 2) trunk_fwd(Args a) {
;     extern __shared__ __attribute__((aligned(16))) unsigned char lds_raw[];
amdhsa.kernels:
  - .agpr_count:     0
    .args:
      - .offset:         0
        .size:           112
        .value_kind:     by_value
      - .offset:         112
        .size:           4
        .value_kind:     hidden_block_count_x
      - .offset:         116
        .size:           4
        .value_kind:     hidden_block_count_y
      - .offset:         120
        .size:           4
        .value_kind:     hidden_block_count_z
      - .offset:         124
        .size:           2
        .value_kind:     hidden_group_size_x
      - .offset:         126
        .size:           2
        .value_kind:     hidden_group_size_y
      - .offset:         128
        .size:           2
        .value_kind:     hidden_group_size_z
      - .offset:         130
        .size:           2
        .value_kind:     hidden_remainder_x
      - .offset:         132
        .size:           2
        .value_kind:     hidden_remainder_y
      - .offset:         134
        .size:           2
        .value_kind:     hidden_remainder_z
      - .offset:         152
        .size:           8
        .value_kind:     hidden_global_offset_x
      - .offset:         160
        .size:           8
        .value_kind:     hidden_global_offset_y
      - .offset:         168
        .size:           8
        .value_kind:     hidden_global_offset_z
      - .offset:         176
        .size:           2
        .value_kind:     hidden_grid_dims
      - .offset:         200
        .size:           8
        .value_kind:     hidden_multigrid_sync_arg
      - .offset:         232
        .size:           4
        .value_kind:     hidden_dynamic_lds_size
    .group_segment_fixed_size: 0
    .kernarg_segment_align: 8
    .kernarg_segment_size: 368
    .language:       OpenCL C
    .language_version:
      - 2
      - 0
    .max_flat_workgroup_size: 512
    .name:           _Z9trunk_fwd4Args
    .private_segment_fixed_size: 0
    .sgpr_count:     108
    .sgpr_spill_count: 237
    .symbol:         _Z9trunk_fwd4Args.kd
    .uniform_work_group_size: 1
    .uses_dynamic_stack: false
    .vgpr_count:     256
    .vgpr_spill_count: 0
    .wavefront_size: 64
